# v19: stick-breaking diagonal validity from one subtract + constant compares, 64-bit splat moves
# speedup vs baseline: 1.0980x; 1.0007x over previous
; DI int crow(int r, int hi) { return (r & 3) + 8 * (r >> 2) + 4 * hi; }
; DI float ex2(float x) { return __builtin_amdgcn_exp2f(x); }
; DI float lg2(float x) { return __builtin_amdgcn_logf(x); }
; template <int S> DI bf16x8 pack8(const f32x16& x) { u32x4 p; p[0] = cvtpk(x[8 * S], x[8 * S + 1]); p[1] = cvtpk(x[8 * S + 2], x[8 * S + 3]); p[2] = cvtpk(x[8 * S + 4], x[8 * S + 5]); p[3] = cvtpk(x[8 * S + 6], x[8 * S + 7]); return __builtin_bit_cast(bf16x8, p); }
; DI void sb_unit(LAS char* lds, int b, int h, int qb, const bf16_t* __restrict__ Q, const bf16_t* __restrict__ K, const bf16_t* __restrict__ VT, const bf16_t* __restrict__ G, bf16_t* __restrict__ MIX) {
;     ...
;             for (int r = 0; r < 16; ++r) {
;                 { const float z = p0[r]; const float lg = (z > 30.f) ? z : lg2(1.0f + ex2(z)); const bool valid = !diag || (kv0 + crow(r, hi) < tq); L0[r] = valid ? -lg : 0.f; p0[r] = valid ? (z - lg) : -1e30f; }
;                 { const float z = p1[r]; const float lg = (z > 30.f) ? z : lg2(1.0f + ex2(z)); const bool valid = !diag || (kv0 + 32 + crow(r, hi) < tq); L1[r] = valid ? -lg : 0.f; p1[r] = valid ? (z - lg) : -1e30f; }
;             }
;             const bf16x8 Lh0 = pack8<0>(L0), Lh1 = pack8<1>(L0), Lh2 = pack8<0>(L1), Lh3 = pack8<1>(L1);
.Lsb_sp_diag:
	v_sub_u32_e32 v224, v101, v35
	v_cmp_gt_i32_e64 s[52:53], v224, 0
	v_cmp_gt_i32_e64 s[54:55], v224, 1
	v_cmp_gt_i32_e64 s[56:57], v224, 2
	v_cmp_gt_i32_e64 s[58:59], v224, 3
	v_cmp_gt_i32_e64 s[60:61], v224, 8
	v_cmp_gt_i32_e64 s[62:63], v224, 9
	v_cmp_gt_i32_e64 s[64:65], v224, 10
	v_cmp_gt_i32_e64 s[66:67], v224, 11
	v_cmp_gt_i32_e64 s[68:69], v224, 16
	v_cmp_gt_i32_e64 s[70:71], v224, 17
	v_cndmask_b32_e64 v192, 0, -v160, s[52:53]
	v_cndmask_b32_e64 v193, 0, -v161, s[54:55]
	v_cndmask_b32_e64 v194, 0, -v162, s[56:57]
	v_cndmask_b32_e64 v195, 0, -v163, s[58:59]
	v_cndmask_b32_e64 v196, 0, -v164, s[60:61]
	v_cndmask_b32_e64 v197, 0, -v165, s[62:63]
	v_cndmask_b32_e64 v198, 0, -v166, s[64:65]
	v_cndmask_b32_e64 v199, 0, -v167, s[66:67]
	v_cndmask_b32_e64 v200, 0, -v168, s[68:69]
	v_cndmask_b32_e64 v201, 0, -v169, s[70:71]
	v_sub_f32_e32 v160, v52, v160
	v_sub_f32_e32 v161, v53, v161
	v_sub_f32_e32 v162, v54, v162
	v_sub_f32_e32 v163, v55, v163
	v_sub_f32_e32 v164, v56, v164
	v_sub_f32_e32 v165, v57, v165
	v_sub_f32_e32 v166, v58, v166
	v_sub_f32_e32 v167, v59, v167
	v_sub_f32_e32 v168, v60, v168
	v_sub_f32_e32 v169, v61, v169
	v_cndmask_b32_e64 v108, v237, v160, s[52:53]
	v_cndmask_b32_e64 v111, v237, v161, s[54:55]
	v_cndmask_b32_e64 v113, v237, v162, s[56:57]
	v_cndmask_b32_e64 v115, v237, v163, s[58:59]
	v_cndmask_b32_e64 v117, v237, v164, s[60:61]
	v_cndmask_b32_e64 v119, v237, v165, s[62:63]
	v_cndmask_b32_e64 v121, v237, v166, s[64:65]
	v_cndmask_b32_e64 v123, v237, v167, s[66:67]
	v_cndmask_b32_e64 v125, v237, v168, s[68:69]
	v_cndmask_b32_e64 v127, v237, v169, s[70:71]
	v_cmp_gt_i32_e64 s[52:53], v224, 18
	v_cmp_gt_i32_e64 s[54:55], v224, 19
	v_cmp_gt_i32_e64 s[56:57], v224, 24
	v_cmp_gt_i32_e64 s[58:59], v224, 25
	v_cmp_gt_i32_e64 s[60:61], v224, 26
	v_cmp_gt_i32_e64 s[62:63], v224, 27
	v_cmp_gt_i32_e64 s[64:65], v224, 32
	v_cmp_gt_i32_e64 s[66:67], v224, 33
	v_cmp_gt_i32_e64 s[68:69], v224, 34
	v_cmp_gt_i32_e64 s[70:71], v224, 35
	v_cndmask_b32_e64 v202, 0, -v170, s[52:53]
	v_cndmask_b32_e64 v203, 0, -v171, s[54:55]
	v_cndmask_b32_e64 v204, 0, -v172, s[56:57]
	v_cndmask_b32_e64 v205, 0, -v173, s[58:59]
	v_cndmask_b32_e64 v206, 0, -v174, s[60:61]
	v_cndmask_b32_e64 v207, 0, -v175, s[62:63]
	v_cndmask_b32_e64 v208, 0, -v176, s[64:65]
	v_cndmask_b32_e64 v209, 0, -v177, s[66:67]
	v_cndmask_b32_e64 v210, 0, -v178, s[68:69]
	v_cndmask_b32_e64 v211, 0, -v179, s[70:71]
	v_sub_f32_e32 v170, v62, v170
	v_sub_f32_e32 v171, v63, v171
	v_sub_f32_e32 v172, v64, v172
	v_sub_f32_e32 v173, v65, v173
	v_sub_f32_e32 v174, v66, v174
	v_sub_f32_e32 v175, v67, v175
	v_sub_f32_e32 v176, v36, v176
	v_sub_f32_e32 v177, v37, v177
	v_sub_f32_e32 v178, v38, v178
	v_sub_f32_e32 v179, v39, v179
	v_cndmask_b32_e64 v129, v237, v170, s[52:53]
	v_cndmask_b32_e64 v131, v237, v171, s[54:55]
	v_cndmask_b32_e64 v133, v237, v172, s[56:57]
	v_cndmask_b32_e64 v135, v237, v173, s[58:59]
	v_cndmask_b32_e64 v66, v237, v174, s[60:61]
	v_cndmask_b32_e64 v155, v237, v175, s[62:63]
	v_cndmask_b32_e64 v110, v237, v176, s[64:65]
	v_cndmask_b32_e64 v112, v237, v177, s[66:67]
	v_cndmask_b32_e64 v114, v237, v178, s[68:69]
	v_cndmask_b32_e64 v116, v237, v179, s[70:71]
	v_cmp_gt_i32_e64 s[52:53], v224, 40
	v_cmp_gt_i32_e64 s[54:55], v224, 41
	v_cmp_gt_i32_e64 s[56:57], v224, 42
	v_cmp_gt_i32_e64 s[58:59], v224, 43
	v_cmp_gt_i32_e64 s[60:61], v224, 48
	v_cmp_gt_i32_e64 s[62:63], v224, 49
	v_cmp_gt_i32_e64 s[64:65], v224, 50
	v_cmp_gt_i32_e64 s[66:67], v224, 51
	v_cmp_gt_i32_e64 s[68:69], v224, 56
	v_cmp_gt_i32_e64 s[70:71], v224, 57
	v_cndmask_b32_e64 v212, 0, -v180, s[52:53]
	v_cndmask_b32_e64 v213, 0, -v181, s[54:55]
	v_cndmask_b32_e64 v214, 0, -v182, s[56:57]
	v_cndmask_b32_e64 v215, 0, -v183, s[58:59]
	v_cndmask_b32_e64 v216, 0, -v184, s[60:61]
	v_cndmask_b32_e64 v217, 0, -v185, s[62:63]
	v_cndmask_b32_e64 v218, 0, -v186, s[64:65]
	v_cndmask_b32_e64 v219, 0, -v187, s[66:67]
	v_cndmask_b32_e64 v220, 0, -v188, s[68:69]
	v_cndmask_b32_e64 v221, 0, -v189, s[70:71]
	v_sub_f32_e32 v180, v40, v180
	v_sub_f32_e32 v181, v41, v181
	v_sub_f32_e32 v182, v42, v182
	v_sub_f32_e32 v183, v43, v183
	v_sub_f32_e32 v184, v44, v184
	v_sub_f32_e32 v185, v45, v185
	v_sub_f32_e32 v186, v46, v186
	v_sub_f32_e32 v187, v47, v187
	v_sub_f32_e32 v188, v48, v188
	v_sub_f32_e32 v189, v49, v189
	v_cndmask_b32_e64 v118, v237, v180, s[52:53]
	v_cndmask_b32_e64 v120, v237, v181, s[54:55]
	v_cndmask_b32_e64 v122, v237, v182, s[56:57]
	v_cndmask_b32_e64 v124, v237, v183, s[58:59]
	v_cndmask_b32_e64 v126, v237, v184, s[60:61]
	v_cndmask_b32_e64 v128, v237, v185, s[62:63]
	v_cndmask_b32_e64 v130, v237, v186, s[64:65]
	v_cndmask_b32_e64 v132, v237, v187, s[66:67]
	v_cndmask_b32_e64 v134, v237, v188, s[68:69]
	v_cndmask_b32_e64 v136, v237, v189, s[70:71]
	v_cmp_gt_i32_e64 s[52:53], v224, 58
	v_cmp_gt_i32_e64 s[54:55], v224, 59
	s_nop 1
	v_cndmask_b32_e64 v222, 0, -v190, s[52:53]
	v_cndmask_b32_e64 v223, 0, -v191, s[54:55]
	v_sub_f32_e32 v190, v50, v190
	v_sub_f32_e32 v191, v51, v191
	v_cndmask_b32_e64 v154, v237, v190, s[52:53]
	v_cndmask_b32_e64 v156, v237, v191, s[54:55]
	v_mov_b32_e32 v109, v192
	v_cvt_pk_bf16_f32 v138, v192, v193
	v_cvt_pk_bf16_f32 v139, v194, v195
	v_cvt_pk_bf16_f32 v140, v196, v197
	v_cvt_pk_bf16_f32 v141, v198, v199
	v_cvt_pk_bf16_f32 v142, v200, v201
	v_cvt_pk_bf16_f32 v143, v202, v203
	v_cvt_pk_bf16_f32 v144, v204, v205
	v_cvt_pk_bf16_f32 v145, v206, v207
	v_cvt_pk_bf16_f32 v146, v208, v209
	v_cvt_pk_bf16_f32 v147, v210, v211
	v_cvt_pk_bf16_f32 v148, v212, v213
	v_cvt_pk_bf16_f32 v149, v214, v215
	v_cvt_pk_bf16_f32 v150, v216, v217
	v_cvt_pk_bf16_f32 v151, v218, v219
	v_cvt_pk_bf16_f32 v152, v220, v221
	v_cvt_pk_bf16_f32 v153, v222, v223
; #define MFMA32(a, b, c) __builtin_amdgcn_mfma_f32_32x32x16_bf16((a), (b), (c), 0, 0, 0)
; DI float ex2(float x) { return __builtin_amdgcn_exp2f(x); }
; template <int S> DI bf16x8 pack8(const f32x16& x) { u32x4 p; p[0] = cvtpk(x[8 * S], x[8 * S + 1]); p[1] = cvtpk(x[8 * S + 2], x[8 * S + 3]); p[2] = cvtpk(x[8 * S + 4], x[8 * S + 5]); p[3] = cvtpk(x[8 * S + 6], x[8 * S + 7]); return __builtin_bit_cast(bf16x8, p); }
; #define SB_PV(ks, pa) { const bf16x8 v0 = ldsv(Vt + off128(r32, 2 * (ks) + hi)), v1 = ldsv(Vt + off128(32 + r32, 2 * (ks) + hi)); o0 = MFMA32(v0, pa, o0); o1 = MFMA32(v1, pa, o1); }
; DI void sb_unit(LAS char* lds, int b, int h, int qb, const bf16_t* __restrict__ Q, const bf16_t* __restrict__ K, const bf16_t* __restrict__ VT, const bf16_t* __restrict__ G, bf16_t* __restrict__ MIX) {
;     ...
;             const bf16x8 Lh0 = pack8<0>(L0), Lh1 = pack8<1>(L0), Lh2 = pack8<0>(L1), Lh3 = pack8<1>(L1);
;             f32x16 C0 = splat16(carry), C1 = C0;
;             C0 = MFMA32(tp0, Lh0, C0); C0 = MFMA32(tp1, Lh1, C0); C0 = MFMA32(ones, Lh2, C0); C0 = MFMA32(ones, Lh3, C0);
;             C1 = MFMA32(tp0, Lh2, C1); C1 = MFMA32(tp1, Lh3, C1);
;             const float cn = C0[0] + L0[0];
;             carry = __shfl(cn, r32, 64);
; #pragma unroll
;             for (int r = 0; r < 16; ++r) { p0[r] = ex2(p0[r] + C0[r]); p1[r] = ex2(p1[r] + C1[r]); }
;             const bf16x8 pa0 = pack8<0>(p0), pa1 = pack8<1>(p0), pa2 = pack8<0>(p1), pa3 = pack8<1>(p1);
;     ...
;             SB_PV(0, pa0) SB_PV(1, pa1) SB_PV(2, pa2) SB_PV(3, pa3)
;     ...
;             done = __all(carry < -152.f) ? 1 : 0;
.Lsb_sp_join:
	s_mov_b32 s0, s4
	v_mov_b32_e32 v35, v34
	v_mov_b64_e32 v[36:37], v[34:35]
	v_mov_b64_e32 v[38:39], v[34:35]
	v_mov_b64_e32 v[40:41], v[34:35]
	v_mov_b64_e32 v[42:43], v[34:35]
	v_mov_b64_e32 v[44:45], v[34:35]
	v_mov_b64_e32 v[46:47], v[34:35]
	v_mov_b64_e32 v[48:49], v[34:35]
	v_writelane_b32 v254, s0, 48
	s_nop 1
	v_mfma_f32_32x32x16_bf16 v[50:65], v[84:87], v[138:141], v[34:49]
	v_mov_b64_e32 v[140:141], s[6:7]
	v_mov_b64_e32 v[138:139], s[4:5]
	v_writelane_b32 v254, s1, 49
	v_writelane_b32 v254, s2, 50
	v_writelane_b32 v254, s3, 51
	s_mov_b32 s0, 0xc3180000
	v_mfma_f32_32x32x16_bf16 v[50:65], v[88:91], v[142:145], v[50:65]
	v_mfma_f32_32x32x16_bf16 v[34:49], v[84:87], v[146:149], v[34:49]
	v_mfma_f32_32x32x16_bf16 v[50:65], v[138:141], v[146:149], v[50:65]
	v_mfma_f32_32x32x16_bf16 v[34:49], v[88:91], v[150:153], v[34:49]
	v_mfma_f32_32x32x16_bf16 v[50:65], v[138:141], v[150:153], v[50:65]
	v_add3_u32 v192, s43, v104, v103
	v_add3_u32 v193, s43, v105, v103
	v_add3_u32 v194, s43, v106, v103
	v_add3_u32 v195, s43, v107, v103
	ds_read_b128 v[160:163], v192 offset:8192
	ds_read_b128 v[164:167], v192 offset:12288
	ds_read_b128 v[168:171], v193 offset:8192
	ds_read_b128 v[172:175], v193 offset:12288
	ds_read_b128 v[176:179], v194 offset:8192
	ds_read_b128 v[180:183], v194 offset:12288
	ds_read_b128 v[184:187], v195 offset:8192
	ds_read_b128 v[188:191], v195 offset:12288
	s_nop 0
	v_add_f32_e32 v38, v118, v38
	v_add_f32_e32 v39, v120, v39
	v_add_f32_e32 v40, v122, v40
	v_add_f32_e32 v42, v126, v42
	v_add_f32_e32 v43, v128, v43
	v_add_f32_e32 v44, v130, v44
	v_add_f32_e32 v45, v132, v45
	v_add_f32_e32 v46, v134, v46
	v_add_f32_e32 v67, v109, v50
	v_and_or_b32 v109, v238, 64, v100
	v_add_f32_e32 v50, v50, v108
	v_add_f32_e32 v54, v54, v117
	v_exp_f32_e32 v108, v38
	v_add_f32_e32 v38, v55, v119
	v_exp_f32_e32 v55, v39
	v_add_f32_e32 v39, v56, v121
	v_exp_f32_e32 v56, v40
	v_add_f32_e32 v40, v57, v123
	v_add_f32_e32 v57, v58, v125
	v_exp_f32_e32 v58, v42
	v_add_f32_e32 v42, v59, v127
	v_exp_f32_e32 v59, v43
	v_add_f32_e32 v43, v60, v129
	v_exp_f32_e32 v60, v44
	v_add_f32_e32 v44, v61, v131
	v_exp_f32_e32 v61, v45
	v_add_f32_e32 v45, v62, v133
	v_exp_f32_e32 v62, v46
	v_add_f32_e32 v46, v63, v135
	v_lshlrev_b32_e32 v109, 2, v109
	v_add_f32_e32 v51, v51, v111
	v_add_f32_e32 v52, v52, v113
	v_add_f32_e32 v53, v53, v115
	v_exp_f32_e32 v54, v54
	v_exp_f32_e32 v38, v38
	v_add_f32_e32 v41, v124, v41
	v_exp_f32_e32 v63, v46
	v_add_f32_e32 v46, v136, v47
	ds_bpermute_b32 v67, v109, v67
	v_exp_f32_e32 v50, v50
	v_exp_f32_e32 v51, v51
	v_exp_f32_e32 v52, v52
	v_exp_f32_e32 v53, v53
	v_exp_f32_e32 v39, v39
	v_exp_f32_e32 v40, v40
	v_exp_f32_e32 v41, v41
	v_exp_f32_e32 v57, v57
	v_exp_f32_e32 v42, v42
	v_exp_f32_e32 v109, v46
	v_add_f32_e32 v46, v64, v66
	v_exp_f32_e32 v64, v46
	v_add_f32_e32 v46, v154, v48
	v_exp_f32_e32 v66, v46
	v_add_f32_e32 v46, v65, v155
	v_exp_f32_e32 v65, v46
	v_add_f32_e32 v46, v156, v49
	v_cvt_pk_bf16_f32 v48, v54, v38
	v_add_f32_e32 v34, v110, v34
	v_exp_f32_e32 v110, v46
	v_cvt_pk_bf16_f32 v46, v50, v51
	v_cvt_pk_bf16_f32 v47, v52, v53
	v_cvt_pk_bf16_f32 v49, v39, v40
	v_cvt_pk_bf16_f32 v42, v57, v42
	v_cvt_pk_bf16_f32 v40, v108, v55
	v_cvt_pk_bf16_f32 v41, v56, v41
	s_waitcnt lgkmcnt(0)
	v_mfma_f32_32x32x16_bf16 v[18:33], v[160:163], v[46:49], v[18:33]
	v_exp_f32_e32 v43, v43
	v_exp_f32_e32 v44, v44
	v_exp_f32_e32 v45, v45
	v_add_f32_e32 v35, v112, v35
	v_add_f32_e32 v36, v114, v36
	v_cvt_pk_bf16_f32 v43, v43, v44
	s_waitcnt lgkmcnt(0)
	v_mfma_f32_32x32x16_bf16 v[2:17], v[164:167], v[46:49], v[2:17]
	v_cvt_pk_bf16_f32 v44, v45, v63
	v_cvt_pk_bf16_f32 v45, v64, v65
	v_add_f32_e32 v37, v116, v37
	v_exp_f32_e32 v34, v34
	v_exp_f32_e32 v35, v35
	v_exp_f32_e32 v36, v36
	s_waitcnt lgkmcnt(1)
	v_mfma_f32_32x32x16_bf16 v[18:33], v[168:171], v[42:45], v[18:33]
	v_exp_f32_e32 v37, v37
	v_cvt_pk_bf16_f32 v38, v34, v35
	v_cvt_pk_bf16_f32 v34, v58, v59
	v_cvt_pk_bf16_f32 v35, v60, v61
	v_cvt_pk_bf16_f32 v39, v36, v37
	v_cvt_pk_bf16_f32 v36, v62, v109
	s_waitcnt lgkmcnt(0)
	v_mfma_f32_32x32x16_bf16 v[2:17], v[172:175], v[42:45], v[2:17]
	v_cvt_pk_bf16_f32 v37, v66, v110
	v_cmp_gt_f32_e32 vcc, s0, v67
	s_cmp_eq_u64 vcc, exec
	s_cselect_b64 s[0:1], -1, 0
	s_waitcnt lgkmcnt(1)
	v_mfma_f32_32x32x16_bf16 v[18:33], v[176:179], v[38:41], v[18:33]
	s_waitcnt lgkmcnt(0)
	v_mfma_f32_32x32x16_bf16 v[2:17], v[180:183], v[38:41], v[2:17]
	s_waitcnt lgkmcnt(1)
	v_mfma_f32_32x32x16_bf16 v[18:33], v[184:187], v[34:37], v[18:33]
	s_waitcnt lgkmcnt(0)
	v_mfma_f32_32x32x16_bf16 v[2:17], v[188:191], v[34:37], v[2:17]
	v_cndmask_b32_e64 v36, 0, 1, s[0:1]
	v_mov_b32_e32 v34, v67
